# norm phase, context rows with pending split-K partials: the 36 load+vmcnt(0) round trips replaced by two batches of 18 loads with counted waits (same arithmetic order)
# speedup vs baseline: 1.0042x; 1.0042x over previous
.LBB0_656:
	v_mul_f32_e32 v81, v29, v29
	v_mul_f32_e32 v89, v31, v31
	v_fmac_f32_e32 v81, v28, v28
	v_fmac_f32_e32 v89, v30, v30
	v_add_f32_e32 v81, v81, v89
	v_mul_f32_e32 v89, v25, v25
	v_mul_f32_e32 v102, v27, v27
	v_fmac_f32_e32 v89, v24, v24
	v_fmac_f32_e32 v102, v26, v26
	v_add_f32_e32 v89, v89, v102
	v_add_f32_e32 v81, v81, v89
	v_mul_f32_e32 v89, v21, v21
	v_mul_f32_e32 v102, v23, v23
	v_fmac_f32_e32 v89, v20, v20
	v_fmac_f32_e32 v102, v22, v22
	v_add_f32_e32 v89, v89, v102
	v_add_f32_e32 v81, v89, v81
	v_mul_f32_e32 v89, v17, v17
	v_mul_f32_e32 v102, v19, v19
	v_fmac_f32_e32 v89, v16, v16
	v_fmac_f32_e32 v102, v18, v18
	v_add_f32_e32 v89, v89, v102
	s_andn2_b64 vcc, exec, s[2:3]
	v_add_f32_e32 v81, v89, v81
	s_cbranch_vccnz .LBB0_649
	s_cmp_lt_i32 s96, 0x8000
	s_cselect_b64 s[2:3], -1, 0
	s_or_b64 s[2:3], s[48:49], s[2:3]
	s_and_b64 vcc, exec, s[2:3]
	s_cbranch_vccnz .LBB0_649
	s_lshl_b64 s[2:3], s[96:97], 12
	s_addk_i32 s96, 0x8000
	v_lshl_add_u64 v[102:103], v[96:97], 0, s[2:3]
	s_lshl_b64 s[2:3], s[96:97], 12
	v_mov_b32_e32 v89, v88
	s_add_u32 s2, s16, s2
	s_addc_u32 s3, s17, s3
	global_load_dwordx4 v[132:135], v80, s[2:3]
	v_add_u32_e32 v125, 0x800000, v80
	global_load_dwordx4 v[136:139], v125, s[2:3]
	v_add_u32_e32 v124, 0x1000000, v80
	global_load_dwordx4 v[140:143], v124, s[2:3]
	v_add_u32_e32 v125, 0x1800000, v80
	global_load_dwordx4 v[144:147], v125, s[2:3]
	v_add_u32_e32 v124, 0x2000000, v80
	global_load_dwordx4 v[148:151], v124, s[2:3]
	v_add_u32_e32 v125, 0x2800000, v80
	global_load_dwordx4 v[152:155], v125, s[2:3]
	v_add_u32_e32 v124, 0x3000000, v80
	global_load_dwordx4 v[156:159], v124, s[2:3]
	v_add_u32_e32 v125, 0x3800000, v80
	global_load_dwordx4 v[160:163], v125, s[2:3]
	global_load_dwordx4 v[164:167], v[94:95], off
	global_load_dwordx4 v[168:171], v80, s[2:3] offset:1024
	v_add_u32_e32 v125, 0x800000, v80
	global_load_dwordx4 v[172:175], v125, s[2:3] offset:1024
	v_add_u32_e32 v124, 0x1000000, v80
	global_load_dwordx4 v[200:203], v124, s[2:3] offset:1024
	v_add_u32_e32 v125, 0x1800000, v80
	global_load_dwordx4 v[204:207], v125, s[2:3] offset:1024
	v_add_u32_e32 v124, 0x2000000, v80
	global_load_dwordx4 v[208:211], v124, s[2:3] offset:1024
	v_add_u32_e32 v125, 0x2800000, v80
	global_load_dwordx4 v[212:215], v125, s[2:3] offset:1024
	v_add_u32_e32 v124, 0x3000000, v80
	global_load_dwordx4 v[216:219], v124, s[2:3] offset:1024
	v_add_u32_e32 v125, 0x3800000, v80
	global_load_dwordx4 v[220:223], v125, s[2:3] offset:1024
	global_load_dwordx4 v[224:227], v[94:95], off offset:1024
	s_waitcnt vmcnt(9)
	v_pk_add_f32 v[238:239], v[132:133], 0 op_sel_hi:[1,0]
	v_pk_add_f32 v[240:241], v[134:135], 0 op_sel_hi:[1,0]
	v_pk_add_f32 v[238:239], v[238:239], v[136:137]
	v_pk_add_f32 v[240:241], v[240:241], v[138:139]
	v_pk_add_f32 v[238:239], v[238:239], v[140:141]
	v_pk_add_f32 v[240:241], v[240:241], v[142:143]
	v_pk_add_f32 v[238:239], v[238:239], v[144:145]
	v_pk_add_f32 v[240:241], v[240:241], v[146:147]
	v_pk_add_f32 v[238:239], v[238:239], v[148:149]
	v_pk_add_f32 v[240:241], v[240:241], v[150:151]
	v_pk_add_f32 v[238:239], v[238:239], v[152:153]
	v_pk_add_f32 v[240:241], v[240:241], v[154:155]
	v_pk_add_f32 v[238:239], v[238:239], v[156:157]
	v_pk_add_f32 v[240:241], v[240:241], v[158:159]
	v_pk_add_f32 v[238:239], v[238:239], v[160:161]
	v_pk_add_f32 v[240:241], v[240:241], v[162:163]
	v_pk_mul_f32 v[166:167], v[88:89], v[166:167]
	v_pk_mul_f32 v[164:165], v[90:91], v[164:165]
	v_pk_fma_f32 v[30:31], v[240:241], v[166:167], v[30:31]
	v_pk_fma_f32 v[28:29], v[238:239], v[164:165], v[28:29]
	v_pk_mul_f32 v[104:105], v[30:31], v[30:31]
	v_pk_mul_f32 v[106:107], v[28:29], v[28:29]
	global_store_dwordx4 v[102:103], v[28:31], off
	v_pk_mov_b32 v[114:115], v[106:107], v[104:105] op_sel:[1,0]
	v_mov_b32_e32 v107, v105
	v_pk_add_f32 v[104:105], v[114:115], v[106:107]
	s_waitcnt vmcnt(1)
	v_pk_add_f32 v[238:239], v[168:169], 0 op_sel_hi:[1,0]
	v_pk_add_f32 v[240:241], v[170:171], 0 op_sel_hi:[1,0]
	v_pk_add_f32 v[238:239], v[238:239], v[172:173]
	v_pk_add_f32 v[240:241], v[240:241], v[174:175]
	v_pk_add_f32 v[238:239], v[238:239], v[200:201]
	v_pk_add_f32 v[240:241], v[240:241], v[202:203]
	v_pk_add_f32 v[238:239], v[238:239], v[204:205]
	v_pk_add_f32 v[240:241], v[240:241], v[206:207]
	v_pk_add_f32 v[238:239], v[238:239], v[208:209]
	v_pk_add_f32 v[240:241], v[240:241], v[210:211]
	v_pk_add_f32 v[238:239], v[238:239], v[212:213]
	v_pk_add_f32 v[240:241], v[240:241], v[214:215]
	v_pk_add_f32 v[238:239], v[238:239], v[216:217]
	v_pk_add_f32 v[240:241], v[240:241], v[218:219]
	v_pk_add_f32 v[238:239], v[238:239], v[220:221]
	v_pk_add_f32 v[240:241], v[240:241], v[222:223]
	v_pk_mul_f32 v[226:227], v[88:89], v[226:227]
	v_pk_mul_f32 v[224:225], v[90:91], v[224:225]
	v_pk_fma_f32 v[26:27], v[240:241], v[226:227], v[26:27]
	v_pk_fma_f32 v[24:25], v[238:239], v[224:225], v[24:25]
	v_pk_mul_f32 v[106:107], v[26:27], v[26:27]
	v_pk_mul_f32 v[114:115], v[24:25], v[24:25]
	global_store_dwordx4 v[102:103], v[24:27], off offset:1024
	v_pk_mov_b32 v[116:117], v[114:115], v[106:107] op_sel:[1,0]
	v_mov_b32_e32 v115, v107
	v_pk_add_f32 v[106:107], v[116:117], v[114:115]
	global_load_dwordx4 v[132:135], v80, s[2:3] offset:2048
	v_add_u32_e32 v125, 0x800000, v80
	global_load_dwordx4 v[136:139], v125, s[2:3] offset:2048
	v_add_u32_e32 v124, 0x1000000, v80
	global_load_dwordx4 v[140:143], v124, s[2:3] offset:2048
	v_add_u32_e32 v125, 0x1800000, v80
	global_load_dwordx4 v[144:147], v125, s[2:3] offset:2048
	v_add_u32_e32 v124, 0x2000000, v80
	global_load_dwordx4 v[148:151], v124, s[2:3] offset:2048
	v_add_u32_e32 v125, 0x2800000, v80
	global_load_dwordx4 v[152:155], v125, s[2:3] offset:2048
	v_add_u32_e32 v124, 0x3000000, v80
	global_load_dwordx4 v[156:159], v124, s[2:3] offset:2048
	v_add_u32_e32 v125, 0x3800000, v80
	global_load_dwordx4 v[160:163], v125, s[2:3] offset:2048
	global_load_dwordx4 v[164:167], v[94:95], off offset:2048
	global_load_dwordx4 v[168:171], v80, s[2:3] offset:3072
	v_add_u32_e32 v125, 0x800000, v80
	global_load_dwordx4 v[172:175], v125, s[2:3] offset:3072
	v_add_u32_e32 v124, 0x1000000, v80
	global_load_dwordx4 v[200:203], v124, s[2:3] offset:3072
	v_add_u32_e32 v125, 0x1800000, v80
	global_load_dwordx4 v[204:207], v125, s[2:3] offset:3072
	v_add_u32_e32 v124, 0x2000000, v80
	global_load_dwordx4 v[208:211], v124, s[2:3] offset:3072
	v_add_u32_e32 v125, 0x2800000, v80
	global_load_dwordx4 v[212:215], v125, s[2:3] offset:3072
	v_add_u32_e32 v124, 0x3000000, v80
	global_load_dwordx4 v[216:219], v124, s[2:3] offset:3072
	v_add_u32_e32 v125, 0x3800000, v80
	global_load_dwordx4 v[220:223], v125, s[2:3] offset:3072
	global_load_dwordx4 v[224:227], v[94:95], off offset:3072
	s_waitcnt vmcnt(9)
	v_pk_add_f32 v[238:239], v[132:133], 0 op_sel_hi:[1,0]
	v_pk_add_f32 v[240:241], v[134:135], 0 op_sel_hi:[1,0]
	v_pk_add_f32 v[238:239], v[238:239], v[136:137]
	v_pk_add_f32 v[240:241], v[240:241], v[138:139]
	v_pk_add_f32 v[238:239], v[238:239], v[140:141]
	v_pk_add_f32 v[240:241], v[240:241], v[142:143]
	v_pk_add_f32 v[238:239], v[238:239], v[144:145]
	v_pk_add_f32 v[240:241], v[240:241], v[146:147]
	v_pk_add_f32 v[238:239], v[238:239], v[148:149]
	v_pk_add_f32 v[240:241], v[240:241], v[150:151]
	v_pk_add_f32 v[238:239], v[238:239], v[152:153]
	v_pk_add_f32 v[240:241], v[240:241], v[154:155]
	v_pk_add_f32 v[238:239], v[238:239], v[156:157]
	v_pk_add_f32 v[240:241], v[240:241], v[158:159]
	v_pk_add_f32 v[238:239], v[238:239], v[160:161]
	v_pk_add_f32 v[240:241], v[240:241], v[162:163]
	v_pk_mul_f32 v[166:167], v[88:89], v[166:167]
	v_pk_mul_f32 v[164:165], v[90:91], v[164:165]
	v_pk_fma_f32 v[22:23], v[240:241], v[166:167], v[22:23]
	v_pk_fma_f32 v[20:21], v[238:239], v[164:165], v[20:21]
	global_store_dwordx4 v[102:103], v[20:23], off offset:2048
	s_waitcnt vmcnt(1)
	v_pk_add_f32 v[238:239], v[168:169], 0 op_sel_hi:[1,0]
	v_pk_add_f32 v[240:241], v[170:171], 0 op_sel_hi:[1,0]
	v_pk_add_f32 v[238:239], v[238:239], v[172:173]
	v_pk_add_f32 v[240:241], v[240:241], v[174:175]
	v_pk_add_f32 v[238:239], v[238:239], v[200:201]
	v_pk_add_f32 v[240:241], v[240:241], v[202:203]
	v_pk_add_f32 v[238:239], v[238:239], v[204:205]
	v_pk_add_f32 v[240:241], v[240:241], v[206:207]
	v_pk_add_f32 v[238:239], v[238:239], v[208:209]
	v_pk_add_f32 v[240:241], v[240:241], v[210:211]
	v_pk_add_f32 v[238:239], v[238:239], v[212:213]
	v_pk_add_f32 v[240:241], v[240:241], v[214:215]
	v_pk_add_f32 v[238:239], v[238:239], v[216:217]
	v_pk_add_f32 v[240:241], v[240:241], v[218:219]
	v_pk_add_f32 v[238:239], v[238:239], v[220:221]
	v_pk_add_f32 v[240:241], v[240:241], v[222:223]
	v_pk_mul_f32 v[226:227], v[88:89], v[226:227]
	v_pk_mul_f32 v[224:225], v[90:91], v[224:225]
	v_pk_fma_f32 v[18:19], v[240:241], v[226:227], v[18:19]
	v_pk_fma_f32 v[16:17], v[238:239], v[224:225], v[16:17]
	global_store_dwordx4 v[102:103], v[16:19], off offset:3072
	v_mul_f32_e32 v81, v16, v16
	v_mul_f32_e32 v89, v17, v17
	v_pk_add_f32 v[102:103], v[104:105], v[104:105] op_sel:[0,1] op_sel_hi:[1,0]
	v_pk_add_f32 v[104:105], v[106:107], v[106:107] op_sel:[0,1] op_sel_hi:[1,0]
	v_mov_b32_e32 v103, v81
	v_mov_b32_e32 v105, v89
	v_pk_add_f32 v[102:103], v[102:103], v[104:105]
	v_mul_f32_e32 v104, v21, v21
	v_mul_f32_e32 v106, v23, v23
	v_mul_f32_e32 v113, v18, v18
	v_mul_f32_e32 v114, v19, v19
	v_pk_fma_f32 v[104:105], v[20:21], v[20:21], v[104:105] op_sel_hi:[1,1,0]
	v_pk_fma_f32 v[106:107], v[22:23], v[22:23], v[106:107] op_sel_hi:[1,1,0]
	v_mov_b32_e32 v105, v113
	v_mov_b32_e32 v107, v114
	v_pk_add_f32 v[104:105], v[104:105], v[106:107]
	s_nop 0
	v_pk_add_f32 v[102:103], v[102:103], v[104:105]
	s_nop 0
	v_add_f32_e32 v81, v102, v103
	s_branch .LBB0_649
